# first grid sync after weight prep done with the kernel's own XCD barrier instead of cooperative-groups sync
# speedup vs baseline: 1.0059x; 1.0059x over previous
; #define LAS __attribute__((address_space(3)))
; __global__ void __launch_bounds__(256, 2) mega_kernel(Params p) {
;     ...
;   cg::grid_group grid = cg::this_grid();
;   if (threadIdx.x == 0) xb_words = make_uint4(0u, 0u, 0u, 0u);
;   __syncthreads();
;   const XcdBarrier xb = xcd_barrier_post((unsigned*)(p.ws + OFF_BAR), (volatile LAS unsigned*)&xb_words);
;   phase_prep(p, smem);
;   grid.sync();
; #pragma unroll 1
;   for (int step = 0; step < 2 + NCHUNK * 17; ++step) {
;     int ph, l, c = 0;
;     if (step < 2) { ph = PH_MEMKV; l = step; }
;     else { const int s = step - 2; c = s / 17; const int r = s - c * 17; if (r == 0) { ph = PH_CONVERT; l = 0; } else { l = (r - 1) >> 3; ph = PH_INPROJ + ((r - 1) & 7); } }
.LBB1_168:
	s_or_b64 exec, exec, s[0:1]
	v_lshrrev_b32_e32 v1, 20, v0
	v_lshrrev_b32_e32 v0, 10, v0
	v_or_b32_e32 v0, v0, v1
	s_movk_i32 s0, 0x3ff
	v_and_or_b32 v0, v0, s0, v172
	v_cmp_eq_u32_e32 vcc, 0, v0
	s_barrier
	s_and_saveexec_b64 s[0:1], vcc
	s_branch .LBB1_178
.LBB1_178:
	s_or_b64 exec, exec, s[0:1]
	s_mul_i32 s0, s79, s78
	s_lshl_b32 s56, s78, 2
	s_lshl_b32 s57, s78, 8
	s_mul_i32 s58, s0, s3
	s_add_u32 s0, s76, 0x1c140200
	s_addc_u32 s1, s77, 0
	v_writelane_b32 v254, s0, 34
	v_exp_f32_e32 v173, 0xbf549a78
	v_exp_f32_e32 v252, 0xbfd49a78
	v_writelane_b32 v254, s1, 35
	s_add_u32 s0, s76, 0x1c140400
	s_addc_u32 s1, s77, 0
	v_writelane_b32 v254, s0, 36
	v_exp_f32_e32 v253, 0xc01f73da
	v_exp_f32_e32 v192, 0xc0549a78
	v_writelane_b32 v254, s1, 37
	s_add_u32 s0, s76, 0x1c140500
	s_addc_u32 s1, s77, 0
	v_writelane_b32 v254, s0, 38
	v_exp_f32_e32 v195, 0xc084e08b
	v_exp_f32_e32 v178, 0xc09f73da
	v_writelane_b32 v254, s1, 39
	s_add_u32 s0, s76, 0x1c140600
	s_addc_u32 s1, s77, 0
	v_writelane_b32 v254, s0, 40
	v_exp_f32_e32 v179, 0xc0ba0729
	v_exp_f32_e32 v180, 0xc0d49a78
	v_writelane_b32 v254, s1, 41
	s_add_u32 s0, s76, 0x1c140700
	s_addc_u32 s1, s77, 0
	v_writelane_b32 v254, s0, 42
	v_exp_f32_e32 v181, 0xc0ef2dc7
	v_exp_f32_e32 v182, 0xc104e08b
	v_writelane_b32 v254, s1, 43
	s_add_u32 s0, s76, 0x1c140800
	s_addc_u32 s1, s77, 0
	s_add_u32 s62, s76, 0x1c140900
	s_addc_u32 s63, s77, 0
	s_add_u32 s64, s76, 0x1c140a00
	s_addc_u32 s65, s77, 0
	s_add_u32 s66, s76, 0x1c140b00
	s_addc_u32 s67, s77, 0
	s_add_u32 s68, s76, 0x1c140c00
	s_addc_u32 s69, s77, 0
	s_add_u32 s70, s76, 0x1c140d00
	s_addc_u32 s71, s77, 0
	s_add_u32 s72, s76, 0x1c140e00
	s_addc_u32 s73, s77, 0
	s_add_u32 s80, s76, 0x1c140f00
	s_addc_u32 s81, s77, 0
	s_add_u32 s82, s76, 0x1c141000
	s_addc_u32 s83, s77, 0
	s_add_u32 s84, s76, 0x1c141100
	s_addc_u32 s85, s77, 0
	s_add_u32 s86, s76, 0x1c141200
	s_addc_u32 s87, s77, 0
	s_add_u32 s88, s76, 0x1c141300
	s_addc_u32 s89, s77, 0
	v_writelane_b32 v254, s0, 44
	s_cmp_eq_u32 s2, 15
	v_exp_f32_e32 v183, 0xc1122a32
	v_writelane_b32 v254, s1, 45
	s_cselect_b64 s[0:1], -1, 0
	v_writelane_b32 v254, s0, 46
	s_cmp_eq_u32 s2, 14
	v_exp_f32_e32 v184, 0xc11f73da
	v_writelane_b32 v254, s1, 47
	s_cselect_b64 s[0:1], -1, 0
	v_writelane_b32 v254, s0, 48
	s_cmp_eq_u32 s2, 13
	v_exp_f32_e32 v185, 0xc12cbd82
	v_writelane_b32 v254, s1, 49
	s_cselect_b64 s[0:1], -1, 0
	v_writelane_b32 v254, s0, 50
	s_cmp_eq_u32 s2, 12
	v_exp_f32_e32 v186, 0xc13a0729
	v_writelane_b32 v254, s1, 51
	s_cselect_b64 s[0:1], -1, 0
	v_writelane_b32 v254, s0, 52
	s_cmp_eq_u32 s2, 11
	v_exp_f32_e32 v187, 0xc14750d0
	v_writelane_b32 v254, s1, 53
	s_cselect_b64 s[0:1], -1, 0
	v_writelane_b32 v254, s0, 54
	s_cmp_eq_u32 s2, 10
	v_mbcnt_lo_u32_b32 v0, -1, 0
	v_writelane_b32 v254, s1, 55
	s_cselect_b64 s[0:1], -1, 0
	v_writelane_b32 v254, s0, 56
	s_cmp_eq_u32 s2, 9
	v_mbcnt_hi_u32_b32 v193, -1, v0
	v_writelane_b32 v254, s1, 57
	s_cselect_b64 s[0:1], -1, 0
	v_writelane_b32 v254, s0, 58
	s_cmp_eq_u32 s2, 8
	v_and_b32_e32 v0, 64, v193
	v_writelane_b32 v254, s1, 59
	s_cselect_b64 s[0:1], -1, 0
	v_writelane_b32 v254, s0, 60
	s_cmp_eq_u32 s2, 7
	v_mov_b32_e32 v1, 0
	v_writelane_b32 v254, s1, 61
	s_cselect_b64 s[0:1], -1, 0
	v_writelane_b32 v254, s0, 62
	s_cmp_eq_u32 s2, 6
	s_movk_i32 s91, 0x48
	v_writelane_b32 v254, s1, 63
	s_cselect_b64 s[0:1], -1, 0
	v_writelane_b32 v255, s0, 0
	s_cmp_eq_u32 s2, 5
	s_mov_b32 s90, 0xfffffc0
	v_writelane_b32 v255, s1, 1
	s_cselect_b64 s[0:1], -1, 0
	v_writelane_b32 v255, s0, 2
	s_cmp_eq_u32 s2, 4
	s_movk_i32 s4, 0x90
	v_writelane_b32 v255, s1, 3
	s_cselect_b64 s[0:1], -1, 0
	v_writelane_b32 v255, s0, 4
	s_cmp_eq_u32 s2, 3
	s_movk_i32 s5, 0x210
	v_writelane_b32 v255, s1, 5
	s_cselect_b64 s[0:1], -1, 0
	v_writelane_b32 v255, s0, 6
	s_cmp_eq_u32 s2, 2
	s_movk_i32 s60, 0xf800
	v_writelane_b32 v255, s1, 7
	s_cselect_b64 s[0:1], -1, 0
	v_writelane_b32 v255, s0, 8
	s_cmp_eq_u32 s2, 1
	v_mov_b32_e32 v188, 0x358637bd
	v_writelane_b32 v255, s1, 9
	s_cselect_b64 s[0:1], -1, 0
	v_writelane_b32 v255, s0, 10
	s_cmp_eq_u32 s2, 0
	v_mov_b32_e32 v189, 0x12200
	v_writelane_b32 v255, s1, 11
	s_cselect_b64 s[0:1], -1, 0
	v_writelane_b32 v255, s0, 12
	v_mov_b32_e32 v190, 0x12204
	v_mov_b32_e32 v191, 1
	v_writelane_b32 v255, s1, 13
	s_lshl_b32 s0, s2, 8
	s_add_u32 s0, s20, s0
	s_addc_u32 s1, s21, 0
	s_add_u32 s2, s0, 0x1400
	s_addc_u32 s3, s1, 0
	v_writelane_b32 v255, s2, 14
	s_add_u32 s0, s0, 0x2400
	s_addc_u32 s1, s1, 0
	v_writelane_b32 v255, s3, 15
	v_writelane_b32 v255, s0, 16
	v_add_u32_e32 v194, 64, v0
	v_xor_b32_e32 v196, 16, v193
	v_writelane_b32 v255, s1, 17
	s_add_u32 s0, s76, 0x1c143400
	s_addc_u32 s1, s77, 0
	v_writelane_b32 v255, s0, 18
	v_xor_b32_e32 v197, 8, v193
	v_xor_b32_e32 v198, 4, v193
	v_writelane_b32 v255, s1, 19
	s_add_u32 s0, s76, 0x1c143500
	s_addc_u32 s1, s77, 0
	v_writelane_b32 v255, s0, 20
	s_lshl_b32 s59, s78, 17
	s_lshl_b32 s95, s78, 7
	v_writelane_b32 v255, s1, 21
	s_lshl_b32 s0, s78, 19
	v_writelane_b32 v255, s0, 22
	v_writelane_b32 v255, s92, 23
	v_writelane_b32 v255, s56, 24
	v_writelane_b32 v255, s57, 25
	v_writelane_b32 v255, s58, 26
	v_xor_b32_e32 v199, 2, v193
	v_xor_b32_e32 v200, 1, v193
	v_mov_b32_e32 v201, 0x12000
	v_mov_b32_e32 v202, 0xff800000
	v_mov_b32_e32 v203, 0xc0
	v_mov_b32_e32 v204, 0x12080
	v_mov_b32_e32 v205, 0x12100
	v_mov_b32_e32 v206, 0x12180
	v_mov_b32_e32 v207, 0x3e0293ee
	s_mov_b32 s38, 0x20000
	s_mov_b32 s39, 0x800000
	s_mov_b32 s96, 0x19140000
	s_mov_b32 s97, 0x2980000
	s_movk_i32 s3, 0x110
	s_mov_b32 s7, 0xff800000
	s_movk_i32 s33, 0x41
	s_mov_b32 s6, -1
	s_mov_b32 s1, 0
	s_mov_b64 s[8:9], 0x80
	s_mov_b64 s[10:11], 0x18000
	v_writelane_b32 v255, s59, 27
	s_barrier
	s_branch .LBB1_181

; #define GAS __attribute__((address_space(1)))
; DI Chunk make_chunk(int c) {
;   Chunk k;
;   if (c < 2) { k.S = 4096; k.sshift = 12; k.nb = 4; k.tok0 = c * CT; k.mb0 = c * 4; }
;   else { k.S = 2048; k.sshift = 11; k.nb = 8; k.tok0 = 32768 + (c - 2) * CT; k.mb0 = 8 + (c - 2) * 8; }
;   return k;
; }
; __global__ void __launch_bounds__(256, 2) mega_kernel(Params p) {
;     ...
;   for (int step = 0; step < 2 + NCHUNK * 17; ++step) {
;     int ph, l, c = 0;
;     if (step < 2) { ph = PH_MEMKV; l = step; }
;     else { const int s = step - 2; c = s / 17; const int r = s - c * 17; if (r == 0) { ph = PH_CONVERT; l = 0; } else { l = (r - 1) >> 3; ph = PH_INPROJ + ((r - 1) & 7); } }
;     GAS const float* xp = (GAS const float*)p.x_prompt; GAS const float* xs = (GAS const float*)p.x_sample; GAS const float* mp = (GAS const float*)p.mem_prompt;
;     GAS const float* ms = (GAS const float*)p.mem_sample; GAS float* po = (GAS float*)p.out; GAS char* pw = (GAS char*)p.ws;
;     asm volatile("" : "+s"(xp), "+s"(xs), "+s"(mp), "+s"(ms), "+s"(po), "+s"(pw));
;     Params q{};
;     q.x_prompt = (const float*)xp; q.x_sample = (const float*)xs; q.mem_prompt = (const float*)mp; q.mem_sample = (const float*)ms; q.out = (float*)po; q.ws = (char*)pw;
;     run_phase(q, ph, l, c, smem);
.LBB1_183:
	s_cmp_eq_u32 s6, -1
	s_cbranch_scc1 .LBB1_428
	v_readlane_b32 s40, v254, 2
	v_readlane_b32 s41, v254, 3
	v_readlane_b32 s42, v254, 4
	v_readlane_b32 s43, v254, 5
	v_readlane_b32 s44, v254, 6
	v_readlane_b32 s45, v254, 7
	v_readlane_b32 s46, v254, 8
	v_readlane_b32 s47, v254, 9
	v_readlane_b32 s48, v254, 10
	v_readlane_b32 s49, v254, 11
	v_readlane_b32 s50, v254, 12
	v_readlane_b32 s51, v254, 13
	v_readlane_b32 s52, v254, 14
	v_readlane_b32 s53, v254, 15
	v_readlane_b32 s54, v254, 16
	v_readlane_b32 s55, v254, 17
	s_mov_b64 s[22:23], s[42:43]
	s_mov_b64 s[12:13], s[46:47]
	s_mov_b64 s[24:25], s[40:41]
	s_mov_b64 s[14:15], s[44:45]
	v_readlane_b32 s40, v254, 18
	v_readlane_b32 s54, v254, 32
	v_readlane_b32 s55, v254, 33
	s_mov_b64 s[18:19], s[76:77]
	v_readlane_b32 s46, v254, 24
	s_mov_b64 s[20:21], s[54:55]
	s_cmp_gt_u32 s0, 1
	s_mov_b64 s[26:27], -1
	v_readlane_b32 s41, v254, 19
	v_readlane_b32 s42, v254, 20
	v_readlane_b32 s43, v254, 21
	v_readlane_b32 s44, v254, 22
	v_readlane_b32 s45, v254, 23
	v_readlane_b32 s47, v254, 25
	v_readlane_b32 s48, v254, 26
	v_readlane_b32 s49, v254, 27
	v_readlane_b32 s50, v254, 28
	v_readlane_b32 s51, v254, 29
	v_readlane_b32 s52, v254, 30
	v_readlane_b32 s53, v254, 31
	s_cbranch_scc0 .LBB1_185
	s_add_i32 s2, s0, -2
	s_lshl_b32 s16, s2, 14
	s_lshl_b32 s2, s2, 3
	s_add_i32 s35, s16, 0x8000
	s_add_i32 s46, s2, 8
	s_mov_b64 s[26:27], 0
